# c39: merge epilogue issues the 24 gate-row loads of row groups 0-5 up front instead of one load + wait per fragment
# speedup vs baseline: 1.0127x; 1.0058x over previous
; __device__ __forceinline__ unsigned pk2(float lo, float hi) { f32x2 v = {lo, hi}; bf16x2_t b = __builtin_convertvector(v, bf16x2_t); return __builtin_bit_cast(unsigned, b); }
; __device__ __forceinline__ float bflo(unsigned u) { return __uint_as_float(u << 16); }
; __device__ __forceinline__ float bfhi(unsigned u) { return __uint_as_float(u & 0xffff0000u); }
; __device__ void merge_phase(const Params& p, int l, unsigned char* smem) {
;     ...
;             for (int mi = 0; mi < 8; ++mi) {
;                 const int row = m0 + wm * 128 + mi * 16 + idx;
;                 const float rs = (br == 2) ? rstd[row] : 1.f;
; #pragma unroll
;                 for (int ni = 0; ni < 4; ++ni) {
;                     const int col = n0 + wn * 64 + ni * 16 + 4 * kq;
;                     const u32x2 g = *(const u32x2*)(MG + (size_t)row * 3072 + br * 1024 + col);
;                     f32x4 gv; gv.x = bflo(g.x); gv.y = bfhi(g.x); gv.z = bflo(g.y); gv.w = bfhi(g.y);
;                     f32x4 v = gv * rs * acc[mi][ni];
;                     bf16_t* mp = MR + (size_t)row * 1024 + col;
;                     if (mi < 6) {
;                         if (br > 0) { const u32x2 o = mpk[mi < 6 ? mi : 0][ni]; v.x += bflo(o.x); v.y += bfhi(o.x); v.z += bflo(o.y); v.w += bfhi(o.y); }
;                         u32x2 pk; pk.x = pk2(v.x, v.y); pk.y = pk2(v.z, v.w); mpk[mi < 6 ? mi : 0][ni] = pk;
;                         if (br == 2) *(u32x2*)mp = pk;
.LBB0_1104:
	s_lshl_b32 s9, s90, 11
	v_and_b32_e32 v179, 0xc0, v80
	v_lshrrev_b32_e32 v80, 2, v80
	s_add_u32 s60, s11, s9
	v_and_b32_e32 v80, 12, v80
	s_addc_u32 s61, s12, 0
	v_or3_b32 v80, v179, v80, s88
	v_mov_b64_e32 v[184:185], s[60:61]
	v_mad_i64_i32 v[184:185], s[16:17], v180, s5, v[184:185]
	v_lshlrev_b32_e32 v80, 1, v80
	v_lshl_add_u64 v[184:185], v[184:185], 0, v[80:81]
	s_mov_b32 s100, 0x18000
	s_mov_b32 s101, 0
	global_load_dwordx2 v[190:191], v[184:185], off
	global_load_dwordx2 v[192:193], v[184:185], off offset:32
	global_load_dwordx2 v[194:195], v[184:185], off offset:64
	global_load_dwordx2 v[196:197], v[184:185], off offset:96
	v_lshl_add_u64 v[188:189], v[184:185], 0, s[100:101]
	global_load_dwordx2 v[198:199], v[188:189], off
	global_load_dwordx2 v[200:201], v[188:189], off offset:32
	global_load_dwordx2 v[202:203], v[188:189], off offset:64
	global_load_dwordx2 v[204:205], v[188:189], off offset:96
	v_lshl_add_u64 v[188:189], v[188:189], 0, s[100:101]
	global_load_dwordx2 v[206:207], v[188:189], off
	global_load_dwordx2 v[208:209], v[188:189], off offset:32
	global_load_dwordx2 v[230:231], v[188:189], off offset:64
	global_load_dwordx2 v[232:233], v[188:189], off offset:96
	v_lshl_add_u64 v[188:189], v[188:189], 0, s[100:101]
	global_load_dwordx2 v[234:235], v[188:189], off
	global_load_dwordx2 v[236:237], v[188:189], off offset:32
	global_load_dwordx2 v[238:239], v[188:189], off offset:64
	global_load_dwordx2 v[240:241], v[188:189], off offset:96
	v_lshl_add_u64 v[188:189], v[188:189], 0, s[100:101]
	global_load_dwordx2 v[242:243], v[188:189], off
	global_load_dwordx2 v[244:245], v[188:189], off offset:32
	global_load_dwordx2 v[246:247], v[188:189], off offset:64
	global_load_dwordx2 v[248:249], v[188:189], off offset:96
	v_lshl_add_u64 v[250:251], v[188:189], 0, s[100:101]
	s_cmp_lg_u32 s90, 0
	s_cselect_b64 s[62:63], -1, 0
	s_cmp_eq_u32 s90, 0
	s_waitcnt vmcnt(0)
	v_mov_b32_e32 v186, v190
	v_mov_b32_e32 v187, v191
	v_lshlrev_b32_e32 v188, 16, v186
	v_and_b32_e32 v189, 0xffff0000, v186
	v_lshlrev_b32_e32 v186, 16, v187
	v_and_b32_e32 v187, 0xffff0000, v187
	v_pk_mul_f32 v[188:189], v[182:183], v[188:189] op_sel_hi:[0,1]
	v_pk_mul_f32 v[186:187], v[182:183], v[186:187] op_sel_hi:[0,1]
	v_pk_mul_f32 v[128:129], v[128:129], v[186:187]
	v_pk_mul_f32 v[186:187], v[126:127], v[188:189]
	s_cbranch_scc1 .LBB0_1106
	v_lshlrev_b32_e32 v126, 16, v176
	v_and_b32_e32 v127, 0xffff0000, v176
	v_pk_add_f32 v[186:187], v[186:187], v[126:127]
	v_lshlrev_b32_e32 v126, 16, v177
	v_and_b32_e32 v127, 0xffff0000, v177
	v_pk_add_f32 v[128:129], v[128:129], v[126:127]

; __device__ __forceinline__ unsigned pk2(float lo, float hi) { f32x2 v = {lo, hi}; bf16x2_t b = __builtin_convertvector(v, bf16x2_t); return __builtin_bit_cast(unsigned, b); }
; __device__ __forceinline__ float bflo(unsigned u) { return __uint_as_float(u << 16); }
; __device__ __forceinline__ float bfhi(unsigned u) { return __uint_as_float(u & 0xffff0000u); }
; __device__ void merge_phase(const Params& p, int l, unsigned char* smem) {
;     ...
;             for (int mi = 0; mi < 8; ++mi) {
;                 const int row = m0 + wm * 128 + mi * 16 + idx;
;                 const float rs = (br == 2) ? rstd[row] : 1.f;
; #pragma unroll
;                 for (int ni = 0; ni < 4; ++ni) {
;                     const int col = n0 + wn * 64 + ni * 16 + 4 * kq;
;                     const u32x2 g = *(const u32x2*)(MG + (size_t)row * 3072 + br * 1024 + col);
;                     f32x4 gv; gv.x = bflo(g.x); gv.y = bfhi(g.x); gv.z = bflo(g.y); gv.w = bfhi(g.y);
;                     f32x4 v = gv * rs * acc[mi][ni];
;                     bf16_t* mp = MR + (size_t)row * 1024 + col;
;                     if (mi < 6) {
;                         if (br > 0) { const u32x2 o = mpk[mi < 6 ? mi : 0][ni]; v.x += bflo(o.x); v.y += bfhi(o.x); v.z += bflo(o.y); v.w += bfhi(o.y); }
;                         u32x2 pk; pk.x = pk2(v.x, v.y); pk.y = pk2(v.z, v.w); mpk[mi < 6 ? mi : 0][ni] = pk;
;                         if (br == 2) *(u32x2*)mp = pk;
.LBB0_1108:
	v_mov_b32_e32 v183, v182
	v_mov_b32_e32 v186, v182
	v_mov_b32_e32 v187, v182
	v_cndmask_b32_e64 v179, 0, 1, s[62:63]
	v_cmp_ne_u32_e64 s[38:39], 1, v179
	s_andn2_b64 vcc, exec, s[62:63]
	v_mov_b32_e32 v128, v192
	v_mov_b32_e32 v129, v193
	v_lshlrev_b32_e32 v188, 16, v128
	v_and_b32_e32 v189, 0xffff0000, v128
	v_lshlrev_b32_e32 v128, 16, v129
	v_and_b32_e32 v129, 0xffff0000, v129
	v_pk_mul_f32 v[188:189], v[182:183], v[188:189]
	v_pk_mul_f32 v[128:129], v[186:187], v[128:129]
	v_pk_mul_f32 v[122:123], v[122:123], v[188:189]
	v_pk_mul_f32 v[124:125], v[124:125], v[128:129]
	s_cbranch_vccnz .LBB0_1110
	v_lshlrev_b32_e32 v128, 16, v174
	v_and_b32_e32 v129, 0xffff0000, v174
	v_pk_add_f32 v[122:123], v[122:123], v[128:129]
	v_lshlrev_b32_e32 v128, 16, v175
	v_and_b32_e32 v129, 0xffff0000, v175
	v_pk_add_f32 v[124:125], v[124:125], v[128:129]

; __device__ __forceinline__ unsigned pk2(float lo, float hi) { f32x2 v = {lo, hi}; bf16x2_t b = __builtin_convertvector(v, bf16x2_t); return __builtin_bit_cast(unsigned, b); }
; __device__ __forceinline__ float bflo(unsigned u) { return __uint_as_float(u << 16); }
; __device__ __forceinline__ float bfhi(unsigned u) { return __uint_as_float(u & 0xffff0000u); }
; __device__ void merge_phase(const Params& p, int l, unsigned char* smem) {
;     ...
;             for (int mi = 0; mi < 8; ++mi) {
;                 const int row = m0 + wm * 128 + mi * 16 + idx;
;                 const float rs = (br == 2) ? rstd[row] : 1.f;
; #pragma unroll
;                 for (int ni = 0; ni < 4; ++ni) {
;                     const int col = n0 + wn * 64 + ni * 16 + 4 * kq;
;                     const u32x2 g = *(const u32x2*)(MG + (size_t)row * 3072 + br * 1024 + col);
;                     f32x4 gv; gv.x = bflo(g.x); gv.y = bfhi(g.x); gv.z = bflo(g.y); gv.w = bfhi(g.y);
;                     f32x4 v = gv * rs * acc[mi][ni];
;                     bf16_t* mp = MR + (size_t)row * 1024 + col;
;                     if (mi < 6) {
;                         if (br > 0) { const u32x2 o = mpk[mi < 6 ? mi : 0][ni]; v.x += bflo(o.x); v.y += bfhi(o.x); v.z += bflo(o.y); v.w += bfhi(o.y); }
;                         u32x2 pk; pk.x = pk2(v.x, v.y); pk.y = pk2(v.z, v.w); mpk[mi < 6 ? mi : 0][ni] = pk;
;                         if (br == 2) *(u32x2*)mp = pk;
.LBB0_1112:
	v_mov_b32_e32 v124, v182
	v_mov_b32_e32 v125, v182
	s_and_b64 vcc, exec, s[38:39]
	v_mov_b32_e32 v122, v194
	v_mov_b32_e32 v123, v195
	v_lshlrev_b32_e32 v128, 16, v122
	v_and_b32_e32 v129, 0xffff0000, v122
	v_lshlrev_b32_e32 v122, 16, v123
	v_and_b32_e32 v123, 0xffff0000, v123
	v_pk_mul_f32 v[128:129], v[182:183], v[128:129]
	v_pk_mul_f32 v[122:123], v[124:125], v[122:123]
	v_pk_mul_f32 v[118:119], v[118:119], v[128:129]
	v_pk_mul_f32 v[120:121], v[120:121], v[122:123]
	s_cbranch_vccnz .LBB0_1114
	v_lshlrev_b32_e32 v122, 16, v172
	v_and_b32_e32 v123, 0xffff0000, v172
	v_pk_add_f32 v[118:119], v[118:119], v[122:123]
	v_lshlrev_b32_e32 v122, 16, v173
	v_and_b32_e32 v123, 0xffff0000, v173
	v_pk_add_f32 v[120:121], v[120:121], v[122:123]

; __device__ __forceinline__ unsigned pk2(float lo, float hi) { f32x2 v = {lo, hi}; bf16x2_t b = __builtin_convertvector(v, bf16x2_t); return __builtin_bit_cast(unsigned, b); }
; __device__ __forceinline__ float bflo(unsigned u) { return __uint_as_float(u << 16); }
; __device__ __forceinline__ float bfhi(unsigned u) { return __uint_as_float(u & 0xffff0000u); }
; __device__ void merge_phase(const Params& p, int l, unsigned char* smem) {
;     ...
;             for (int mi = 0; mi < 8; ++mi) {
;                 const int row = m0 + wm * 128 + mi * 16 + idx;
;                 const float rs = (br == 2) ? rstd[row] : 1.f;
; #pragma unroll
;                 for (int ni = 0; ni < 4; ++ni) {
;                     const int col = n0 + wn * 64 + ni * 16 + 4 * kq;
;                     const u32x2 g = *(const u32x2*)(MG + (size_t)row * 3072 + br * 1024 + col);
;                     f32x4 gv; gv.x = bflo(g.x); gv.y = bfhi(g.x); gv.z = bflo(g.y); gv.w = bfhi(g.y);
;                     f32x4 v = gv * rs * acc[mi][ni];
;                     bf16_t* mp = MR + (size_t)row * 1024 + col;
;                     if (mi < 6) {
;                         if (br > 0) { const u32x2 o = mpk[mi < 6 ? mi : 0][ni]; v.x += bflo(o.x); v.y += bfhi(o.x); v.z += bflo(o.y); v.w += bfhi(o.y); }
;                         u32x2 pk; pk.x = pk2(v.x, v.y); pk.y = pk2(v.z, v.w); mpk[mi < 6 ? mi : 0][ni] = pk;
;                         if (br == 2) *(u32x2*)mp = pk;
.LBB0_1116:
	s_and_b64 vcc, exec, s[38:39]
	v_mov_b32_e32 v118, v196
	v_mov_b32_e32 v119, v197
	v_lshlrev_b32_e32 v120, 16, v118
	v_and_b32_e32 v121, 0xffff0000, v118
	v_lshlrev_b32_e32 v118, 16, v119
	v_and_b32_e32 v119, 0xffff0000, v119
	v_pk_mul_f32 v[120:121], v[182:183], v[120:121]
	v_mov_b32_e32 v183, v182
	v_pk_mul_f32 v[118:119], v[182:183], v[118:119]
	v_pk_mul_f32 v[114:115], v[114:115], v[120:121]
	v_pk_mul_f32 v[116:117], v[116:117], v[118:119]
	s_cbranch_vccnz .LBB0_1118
	v_lshlrev_b32_e32 v118, 16, v168
	v_and_b32_e32 v119, 0xffff0000, v168
	v_pk_add_f32 v[114:115], v[114:115], v[118:119]
	v_lshlrev_b32_e32 v118, 16, v169
	v_and_b32_e32 v119, 0xffff0000, v169
	v_pk_add_f32 v[116:117], v[116:117], v[118:119]

; __device__ __forceinline__ unsigned pk2(float lo, float hi) { f32x2 v = {lo, hi}; bf16x2_t b = __builtin_convertvector(v, bf16x2_t); return __builtin_bit_cast(unsigned, b); }
; __device__ __forceinline__ float bflo(unsigned u) { return __uint_as_float(u << 16); }
; __device__ __forceinline__ float bfhi(unsigned u) { return __uint_as_float(u & 0xffff0000u); }
; __device__ void merge_phase(const Params& p, int l, unsigned char* smem) {
;     ...
;             for (int mi = 0; mi < 8; ++mi) {
;                 const int row = m0 + wm * 128 + mi * 16 + idx;
;                 const float rs = (br == 2) ? rstd[row] : 1.f;
; #pragma unroll
;                 for (int ni = 0; ni < 4; ++ni) {
;                     const int col = n0 + wn * 64 + ni * 16 + 4 * kq;
;                     const u32x2 g = *(const u32x2*)(MG + (size_t)row * 3072 + br * 1024 + col);
;                     f32x4 gv; gv.x = bflo(g.x); gv.y = bfhi(g.x); gv.z = bflo(g.y); gv.w = bfhi(g.y);
;                     f32x4 v = gv * rs * acc[mi][ni];
;                     bf16_t* mp = MR + (size_t)row * 1024 + col;
;                     if (mi < 6) {
;                         if (br > 0) { const u32x2 o = mpk[mi < 6 ? mi : 0][ni]; v.x += bflo(o.x); v.y += bfhi(o.x); v.z += bflo(o.y); v.w += bfhi(o.y); }
;                         u32x2 pk; pk.x = pk2(v.x, v.y); pk.y = pk2(v.z, v.w); mpk[mi < 6 ? mi : 0][ni] = pk;
;                         if (br == 2) *(u32x2*)mp = pk;
.LBB0_1122:
	v_mov_b64_e32 v[116:117], s[60:61]
	v_mad_i64_i32 v[116:117], s[16:17], v118, s5, v[116:117]
	v_lshl_add_u64 v[116:117], v[116:117], 0, v[80:81]
	global_load_dwordx2 v[190:191], v[250:251], off
	global_load_dwordx2 v[192:193], v[250:251], off offset:32
	global_load_dwordx2 v[194:195], v[250:251], off offset:64
	global_load_dwordx2 v[196:197], v[250:251], off offset:96
	s_and_b64 vcc, exec, s[38:39]
	s_waitcnt vmcnt(4)
	v_mov_b32_e32 v120, v198
	v_mov_b32_e32 v121, v199
	v_lshlrev_b32_e32 v122, 16, v120
	v_and_b32_e32 v123, 0xffff0000, v120
	v_lshlrev_b32_e32 v120, 16, v121
	v_and_b32_e32 v121, 0xffff0000, v121
	v_pk_mul_f32 v[122:123], v[114:115], v[122:123] op_sel_hi:[0,1]
	v_pk_mul_f32 v[120:121], v[114:115], v[120:121] op_sel_hi:[0,1]
	v_pk_mul_f32 v[112:113], v[112:113], v[120:121]
	v_pk_mul_f32 v[120:121], v[110:111], v[122:123]
	s_cbranch_vccnz .LBB0_1124
	v_lshlrev_b32_e32 v110, 16, v170
	v_and_b32_e32 v111, 0xffff0000, v170
	v_pk_add_f32 v[120:121], v[120:121], v[110:111]
	v_lshlrev_b32_e32 v110, 16, v171
	v_and_b32_e32 v111, 0xffff0000, v171
	v_pk_add_f32 v[112:113], v[112:113], v[110:111]

; __device__ __forceinline__ unsigned pk2(float lo, float hi) { f32x2 v = {lo, hi}; bf16x2_t b = __builtin_convertvector(v, bf16x2_t); return __builtin_bit_cast(unsigned, b); }
; __device__ __forceinline__ float bflo(unsigned u) { return __uint_as_float(u << 16); }
; __device__ __forceinline__ float bfhi(unsigned u) { return __uint_as_float(u & 0xffff0000u); }
; __device__ void merge_phase(const Params& p, int l, unsigned char* smem) {
;     ...
;             for (int mi = 0; mi < 8; ++mi) {
;                 const int row = m0 + wm * 128 + mi * 16 + idx;
;                 const float rs = (br == 2) ? rstd[row] : 1.f;
; #pragma unroll
;                 for (int ni = 0; ni < 4; ++ni) {
;                     const int col = n0 + wn * 64 + ni * 16 + 4 * kq;
;                     const u32x2 g = *(const u32x2*)(MG + (size_t)row * 3072 + br * 1024 + col);
;                     f32x4 gv; gv.x = bflo(g.x); gv.y = bfhi(g.x); gv.z = bflo(g.y); gv.w = bfhi(g.y);
;                     f32x4 v = gv * rs * acc[mi][ni];
;                     bf16_t* mp = MR + (size_t)row * 1024 + col;
;                     if (mi < 6) {
;                         if (br > 0) { const u32x2 o = mpk[mi < 6 ? mi : 0][ni]; v.x += bflo(o.x); v.y += bfhi(o.x); v.z += bflo(o.y); v.w += bfhi(o.y); }
;                         u32x2 pk; pk.x = pk2(v.x, v.y); pk.y = pk2(v.z, v.w); mpk[mi < 6 ? mi : 0][ni] = pk;
;                         if (br == 2) *(u32x2*)mp = pk;
.LBB0_1126:
	v_mov_b32_e32 v115, v114
	v_mov_b32_e32 v118, v114
	v_mov_b32_e32 v119, v114
	s_and_b64 vcc, exec, s[38:39]
	v_mov_b32_e32 v112, v200
	v_mov_b32_e32 v113, v201
	v_lshlrev_b32_e32 v120, 16, v112
	v_and_b32_e32 v121, 0xffff0000, v112
	v_lshlrev_b32_e32 v112, 16, v113
	v_and_b32_e32 v113, 0xffff0000, v113
	v_pk_mul_f32 v[120:121], v[114:115], v[120:121]
	v_pk_mul_f32 v[112:113], v[118:119], v[112:113]
	v_pk_mul_f32 v[106:107], v[106:107], v[120:121]
	v_pk_mul_f32 v[108:109], v[108:109], v[112:113]
	s_cbranch_vccnz .LBB0_1128
	v_lshlrev_b32_e32 v112, 16, v166
	v_and_b32_e32 v113, 0xffff0000, v166
	v_pk_add_f32 v[106:107], v[106:107], v[112:113]
	v_lshlrev_b32_e32 v112, 16, v167
	v_and_b32_e32 v113, 0xffff0000, v167
	v_pk_add_f32 v[108:109], v[108:109], v[112:113]

; __device__ __forceinline__ unsigned pk2(float lo, float hi) { f32x2 v = {lo, hi}; bf16x2_t b = __builtin_convertvector(v, bf16x2_t); return __builtin_bit_cast(unsigned, b); }
; __device__ __forceinline__ float bflo(unsigned u) { return __uint_as_float(u << 16); }
; __device__ __forceinline__ float bfhi(unsigned u) { return __uint_as_float(u & 0xffff0000u); }
; __device__ void merge_phase(const Params& p, int l, unsigned char* smem) {
;     ...
;             for (int mi = 0; mi < 8; ++mi) {
;                 const int row = m0 + wm * 128 + mi * 16 + idx;
;                 const float rs = (br == 2) ? rstd[row] : 1.f;
; #pragma unroll
;                 for (int ni = 0; ni < 4; ++ni) {
;                     const int col = n0 + wn * 64 + ni * 16 + 4 * kq;
;                     const u32x2 g = *(const u32x2*)(MG + (size_t)row * 3072 + br * 1024 + col);
;                     f32x4 gv; gv.x = bflo(g.x); gv.y = bfhi(g.x); gv.z = bflo(g.y); gv.w = bfhi(g.y);
;                     f32x4 v = gv * rs * acc[mi][ni];
;                     bf16_t* mp = MR + (size_t)row * 1024 + col;
;                     if (mi < 6) {
;                         if (br > 0) { const u32x2 o = mpk[mi < 6 ? mi : 0][ni]; v.x += bflo(o.x); v.y += bfhi(o.x); v.z += bflo(o.y); v.w += bfhi(o.y); }
;                         u32x2 pk; pk.x = pk2(v.x, v.y); pk.y = pk2(v.z, v.w); mpk[mi < 6 ? mi : 0][ni] = pk;
;                         if (br == 2) *(u32x2*)mp = pk;
.LBB0_1130:
	v_mov_b32_e32 v108, v114
	v_mov_b32_e32 v109, v114
	s_and_b64 vcc, exec, s[38:39]
	v_mov_b32_e32 v106, v202
	v_mov_b32_e32 v107, v203
	v_lshlrev_b32_e32 v112, 16, v106
	v_and_b32_e32 v113, 0xffff0000, v106
	v_lshlrev_b32_e32 v106, 16, v107
	v_and_b32_e32 v107, 0xffff0000, v107
	v_pk_mul_f32 v[112:113], v[114:115], v[112:113]
	v_pk_mul_f32 v[106:107], v[108:109], v[106:107]
	v_pk_mul_f32 v[102:103], v[102:103], v[112:113]
	v_pk_mul_f32 v[104:105], v[104:105], v[106:107]
	s_cbranch_vccnz .LBB0_1132
	v_lshlrev_b32_e32 v106, 16, v164
	v_and_b32_e32 v107, 0xffff0000, v164
	v_pk_add_f32 v[102:103], v[102:103], v[106:107]
	v_lshlrev_b32_e32 v106, 16, v165
	v_and_b32_e32 v107, 0xffff0000, v165
	v_pk_add_f32 v[104:105], v[104:105], v[106:107]

; __device__ __forceinline__ unsigned pk2(float lo, float hi) { f32x2 v = {lo, hi}; bf16x2_t b = __builtin_convertvector(v, bf16x2_t); return __builtin_bit_cast(unsigned, b); }
; __device__ __forceinline__ float bflo(unsigned u) { return __uint_as_float(u << 16); }
; __device__ __forceinline__ float bfhi(unsigned u) { return __uint_as_float(u & 0xffff0000u); }
; __device__ void merge_phase(const Params& p, int l, unsigned char* smem) {
;     ...
;             for (int mi = 0; mi < 8; ++mi) {
;                 const int row = m0 + wm * 128 + mi * 16 + idx;
;                 const float rs = (br == 2) ? rstd[row] : 1.f;
; #pragma unroll
;                 for (int ni = 0; ni < 4; ++ni) {
;                     const int col = n0 + wn * 64 + ni * 16 + 4 * kq;
;                     const u32x2 g = *(const u32x2*)(MG + (size_t)row * 3072 + br * 1024 + col);
;                     f32x4 gv; gv.x = bflo(g.x); gv.y = bfhi(g.x); gv.z = bflo(g.y); gv.w = bfhi(g.y);
;                     f32x4 v = gv * rs * acc[mi][ni];
;                     bf16_t* mp = MR + (size_t)row * 1024 + col;
;                     if (mi < 6) {
;                         if (br > 0) { const u32x2 o = mpk[mi < 6 ? mi : 0][ni]; v.x += bflo(o.x); v.y += bfhi(o.x); v.z += bflo(o.y); v.w += bfhi(o.y); }
;                         u32x2 pk; pk.x = pk2(v.x, v.y); pk.y = pk2(v.z, v.w); mpk[mi < 6 ? mi : 0][ni] = pk;
;                         if (br == 2) *(u32x2*)mp = pk;
.LBB0_1134:
	s_and_b64 vcc, exec, s[38:39]
	v_mov_b32_e32 v102, v204
	v_mov_b32_e32 v103, v205
	v_lshlrev_b32_e32 v104, 16, v102
	v_and_b32_e32 v105, 0xffff0000, v102
	v_lshlrev_b32_e32 v102, 16, v103
	v_and_b32_e32 v103, 0xffff0000, v103
	v_pk_mul_f32 v[104:105], v[114:115], v[104:105]
	v_mov_b32_e32 v115, v114
	v_pk_mul_f32 v[102:103], v[114:115], v[102:103]
	v_pk_mul_f32 v[98:99], v[98:99], v[104:105]
	v_pk_mul_f32 v[100:101], v[100:101], v[102:103]
	s_cbranch_vccnz .LBB0_1136
	v_lshlrev_b32_e32 v102, 16, v160
	v_and_b32_e32 v103, 0xffff0000, v160
	v_pk_add_f32 v[98:99], v[98:99], v[102:103]
	v_lshlrev_b32_e32 v102, 16, v161
	v_and_b32_e32 v103, 0xffff0000, v161
	v_pk_add_f32 v[100:101], v[100:101], v[102:103]

; __device__ __forceinline__ unsigned pk2(float lo, float hi) { f32x2 v = {lo, hi}; bf16x2_t b = __builtin_convertvector(v, bf16x2_t); return __builtin_bit_cast(unsigned, b); }
; __device__ __forceinline__ float bflo(unsigned u) { return __uint_as_float(u << 16); }
; __device__ __forceinline__ float bfhi(unsigned u) { return __uint_as_float(u & 0xffff0000u); }
; __device__ void merge_phase(const Params& p, int l, unsigned char* smem) {
;     ...
;             for (int mi = 0; mi < 8; ++mi) {
;                 const int row = m0 + wm * 128 + mi * 16 + idx;
;                 const float rs = (br == 2) ? rstd[row] : 1.f;
; #pragma unroll
;                 for (int ni = 0; ni < 4; ++ni) {
;                     const int col = n0 + wn * 64 + ni * 16 + 4 * kq;
;                     const u32x2 g = *(const u32x2*)(MG + (size_t)row * 3072 + br * 1024 + col);
;                     f32x4 gv; gv.x = bflo(g.x); gv.y = bfhi(g.x); gv.z = bflo(g.y); gv.w = bfhi(g.y);
;                     f32x4 v = gv * rs * acc[mi][ni];
;                     bf16_t* mp = MR + (size_t)row * 1024 + col;
;                     if (mi < 6) {
;                         if (br > 0) { const u32x2 o = mpk[mi < 6 ? mi : 0][ni]; v.x += bflo(o.x); v.y += bfhi(o.x); v.z += bflo(o.y); v.w += bfhi(o.y); }
;                         u32x2 pk; pk.x = pk2(v.x, v.y); pk.y = pk2(v.z, v.w); mpk[mi < 6 ? mi : 0][ni] = pk;
;                         if (br == 2) *(u32x2*)mp = pk;
.LBB0_1140:
	v_mov_b64_e32 v[100:101], s[60:61]
	v_mad_i64_i32 v[100:101], s[16:17], v102, s5, v[100:101]
	v_lshl_add_u64 v[100:101], v[100:101], 0, v[80:81]
	s_and_b64 vcc, exec, s[38:39]
	s_waitcnt vmcnt(0)
	v_mov_b32_e32 v104, v206
	v_mov_b32_e32 v105, v207
	v_lshlrev_b32_e32 v106, 16, v104
	v_and_b32_e32 v107, 0xffff0000, v104
	v_lshlrev_b32_e32 v104, 16, v105
	v_and_b32_e32 v105, 0xffff0000, v105
	v_pk_mul_f32 v[106:107], v[98:99], v[106:107] op_sel_hi:[0,1]
	v_pk_mul_f32 v[104:105], v[98:99], v[104:105] op_sel_hi:[0,1]
	v_pk_mul_f32 v[96:97], v[96:97], v[104:105]
	v_pk_mul_f32 v[104:105], v[94:95], v[106:107]
	s_cbranch_vccnz .LBB0_1142
	v_lshlrev_b32_e32 v94, 16, v162
	v_and_b32_e32 v95, 0xffff0000, v162
	v_pk_add_f32 v[104:105], v[104:105], v[94:95]
	v_lshlrev_b32_e32 v94, 16, v163
	v_and_b32_e32 v95, 0xffff0000, v163
	v_pk_add_f32 v[96:97], v[96:97], v[94:95]

; __device__ __forceinline__ unsigned pk2(float lo, float hi) { f32x2 v = {lo, hi}; bf16x2_t b = __builtin_convertvector(v, bf16x2_t); return __builtin_bit_cast(unsigned, b); }
; __device__ __forceinline__ float bflo(unsigned u) { return __uint_as_float(u << 16); }
; __device__ __forceinline__ float bfhi(unsigned u) { return __uint_as_float(u & 0xffff0000u); }
; __device__ void merge_phase(const Params& p, int l, unsigned char* smem) {
;     ...
;             for (int mi = 0; mi < 8; ++mi) {
;                 const int row = m0 + wm * 128 + mi * 16 + idx;
;                 const float rs = (br == 2) ? rstd[row] : 1.f;
; #pragma unroll
;                 for (int ni = 0; ni < 4; ++ni) {
;                     const int col = n0 + wn * 64 + ni * 16 + 4 * kq;
;                     const u32x2 g = *(const u32x2*)(MG + (size_t)row * 3072 + br * 1024 + col);
;                     f32x4 gv; gv.x = bflo(g.x); gv.y = bfhi(g.x); gv.z = bflo(g.y); gv.w = bfhi(g.y);
;                     f32x4 v = gv * rs * acc[mi][ni];
;                     bf16_t* mp = MR + (size_t)row * 1024 + col;
;                     if (mi < 6) {
;                         if (br > 0) { const u32x2 o = mpk[mi < 6 ? mi : 0][ni]; v.x += bflo(o.x); v.y += bfhi(o.x); v.z += bflo(o.y); v.w += bfhi(o.y); }
;                         u32x2 pk; pk.x = pk2(v.x, v.y); pk.y = pk2(v.z, v.w); mpk[mi < 6 ? mi : 0][ni] = pk;
;                         if (br == 2) *(u32x2*)mp = pk;
.LBB0_1144:
	v_mov_b32_e32 v99, v98
	v_mov_b32_e32 v102, v98
	v_mov_b32_e32 v103, v98
	s_and_b64 vcc, exec, s[38:39]
	v_mov_b32_e32 v96, v208
	v_mov_b32_e32 v97, v209
	v_lshlrev_b32_e32 v104, 16, v96
	v_and_b32_e32 v105, 0xffff0000, v96
	v_lshlrev_b32_e32 v96, 16, v97
	v_and_b32_e32 v97, 0xffff0000, v97
	v_pk_mul_f32 v[104:105], v[98:99], v[104:105]
	v_pk_mul_f32 v[96:97], v[102:103], v[96:97]
	v_pk_mul_f32 v[90:91], v[90:91], v[104:105]
	v_pk_mul_f32 v[92:93], v[92:93], v[96:97]
	s_cbranch_vccnz .LBB0_1146
	v_lshlrev_b32_e32 v96, 16, v158
	v_and_b32_e32 v97, 0xffff0000, v158
	v_pk_add_f32 v[90:91], v[90:91], v[96:97]
	v_lshlrev_b32_e32 v96, 16, v159
	v_and_b32_e32 v97, 0xffff0000, v159
	v_pk_add_f32 v[92:93], v[92:93], v[96:97]

; __device__ __forceinline__ unsigned pk2(float lo, float hi) { f32x2 v = {lo, hi}; bf16x2_t b = __builtin_convertvector(v, bf16x2_t); return __builtin_bit_cast(unsigned, b); }
; __device__ __forceinline__ float bflo(unsigned u) { return __uint_as_float(u << 16); }
; __device__ __forceinline__ float bfhi(unsigned u) { return __uint_as_float(u & 0xffff0000u); }
; __device__ void merge_phase(const Params& p, int l, unsigned char* smem) {
;     ...
;             for (int mi = 0; mi < 8; ++mi) {
;                 const int row = m0 + wm * 128 + mi * 16 + idx;
;                 const float rs = (br == 2) ? rstd[row] : 1.f;
; #pragma unroll
;                 for (int ni = 0; ni < 4; ++ni) {
;                     const int col = n0 + wn * 64 + ni * 16 + 4 * kq;
;                     const u32x2 g = *(const u32x2*)(MG + (size_t)row * 3072 + br * 1024 + col);
;                     f32x4 gv; gv.x = bflo(g.x); gv.y = bfhi(g.x); gv.z = bflo(g.y); gv.w = bfhi(g.y);
;                     f32x4 v = gv * rs * acc[mi][ni];
;                     bf16_t* mp = MR + (size_t)row * 1024 + col;
;                     if (mi < 6) {
;                         if (br > 0) { const u32x2 o = mpk[mi < 6 ? mi : 0][ni]; v.x += bflo(o.x); v.y += bfhi(o.x); v.z += bflo(o.y); v.w += bfhi(o.y); }
;                         u32x2 pk; pk.x = pk2(v.x, v.y); pk.y = pk2(v.z, v.w); mpk[mi < 6 ? mi : 0][ni] = pk;
;                         if (br == 2) *(u32x2*)mp = pk;
.LBB0_1148:
	v_mov_b32_e32 v92, v98
	v_mov_b32_e32 v93, v98
	s_and_b64 vcc, exec, s[38:39]
	v_mov_b32_e32 v90, v230
	v_mov_b32_e32 v91, v231
	v_lshlrev_b32_e32 v96, 16, v90
	v_and_b32_e32 v97, 0xffff0000, v90
	v_lshlrev_b32_e32 v90, 16, v91
	v_and_b32_e32 v91, 0xffff0000, v91
	v_pk_mul_f32 v[96:97], v[98:99], v[96:97]
	v_pk_mul_f32 v[90:91], v[92:93], v[90:91]
	v_pk_mul_f32 v[86:87], v[86:87], v[96:97]
	v_pk_mul_f32 v[88:89], v[88:89], v[90:91]
	s_cbranch_vccnz .LBB0_1150
	v_lshlrev_b32_e32 v90, 16, v156
	v_and_b32_e32 v91, 0xffff0000, v156
	v_pk_add_f32 v[86:87], v[86:87], v[90:91]
	v_lshlrev_b32_e32 v90, 16, v157
	v_and_b32_e32 v91, 0xffff0000, v157
	v_pk_add_f32 v[88:89], v[88:89], v[90:91]

; __device__ __forceinline__ unsigned pk2(float lo, float hi) { f32x2 v = {lo, hi}; bf16x2_t b = __builtin_convertvector(v, bf16x2_t); return __builtin_bit_cast(unsigned, b); }
; __device__ __forceinline__ float bflo(unsigned u) { return __uint_as_float(u << 16); }
; __device__ __forceinline__ float bfhi(unsigned u) { return __uint_as_float(u & 0xffff0000u); }
; __device__ void merge_phase(const Params& p, int l, unsigned char* smem) {
;     ...
;             for (int mi = 0; mi < 8; ++mi) {
;                 const int row = m0 + wm * 128 + mi * 16 + idx;
;                 const float rs = (br == 2) ? rstd[row] : 1.f;
; #pragma unroll
;                 for (int ni = 0; ni < 4; ++ni) {
;                     const int col = n0 + wn * 64 + ni * 16 + 4 * kq;
;                     const u32x2 g = *(const u32x2*)(MG + (size_t)row * 3072 + br * 1024 + col);
;                     f32x4 gv; gv.x = bflo(g.x); gv.y = bfhi(g.x); gv.z = bflo(g.y); gv.w = bfhi(g.y);
;                     f32x4 v = gv * rs * acc[mi][ni];
;                     bf16_t* mp = MR + (size_t)row * 1024 + col;
;                     if (mi < 6) {
;                         if (br > 0) { const u32x2 o = mpk[mi < 6 ? mi : 0][ni]; v.x += bflo(o.x); v.y += bfhi(o.x); v.z += bflo(o.y); v.w += bfhi(o.y); }
;                         u32x2 pk; pk.x = pk2(v.x, v.y); pk.y = pk2(v.z, v.w); mpk[mi < 6 ? mi : 0][ni] = pk;
;                         if (br == 2) *(u32x2*)mp = pk;
.LBB0_1152:
	s_and_b64 vcc, exec, s[38:39]
	v_mov_b32_e32 v86, v232
	v_mov_b32_e32 v87, v233
	v_lshlrev_b32_e32 v88, 16, v86
	v_and_b32_e32 v89, 0xffff0000, v86
	v_lshlrev_b32_e32 v86, 16, v87
	v_and_b32_e32 v87, 0xffff0000, v87
	v_pk_mul_f32 v[88:89], v[98:99], v[88:89]
	v_mov_b32_e32 v99, v98
	v_pk_mul_f32 v[86:87], v[98:99], v[86:87]
	v_pk_mul_f32 v[82:83], v[82:83], v[88:89]
	v_pk_mul_f32 v[84:85], v[84:85], v[86:87]
	s_cbranch_vccnz .LBB0_1154
	v_lshlrev_b32_e32 v86, 16, v152
	v_and_b32_e32 v87, 0xffff0000, v152
	v_pk_add_f32 v[82:83], v[82:83], v[86:87]
	v_lshlrev_b32_e32 v86, 16, v153
	v_and_b32_e32 v87, 0xffff0000, v153
	v_pk_add_f32 v[84:85], v[84:85], v[86:87]

; __device__ __forceinline__ unsigned pk2(float lo, float hi) { f32x2 v = {lo, hi}; bf16x2_t b = __builtin_convertvector(v, bf16x2_t); return __builtin_bit_cast(unsigned, b); }
; __device__ __forceinline__ float bflo(unsigned u) { return __uint_as_float(u << 16); }
; __device__ __forceinline__ float bfhi(unsigned u) { return __uint_as_float(u & 0xffff0000u); }
; __device__ void merge_phase(const Params& p, int l, unsigned char* smem) {
;     ...
;             for (int mi = 0; mi < 8; ++mi) {
;                 const int row = m0 + wm * 128 + mi * 16 + idx;
;                 const float rs = (br == 2) ? rstd[row] : 1.f;
; #pragma unroll
;                 for (int ni = 0; ni < 4; ++ni) {
;                     const int col = n0 + wn * 64 + ni * 16 + 4 * kq;
;                     const u32x2 g = *(const u32x2*)(MG + (size_t)row * 3072 + br * 1024 + col);
;                     f32x4 gv; gv.x = bflo(g.x); gv.y = bfhi(g.x); gv.z = bflo(g.y); gv.w = bfhi(g.y);
;                     f32x4 v = gv * rs * acc[mi][ni];
;                     bf16_t* mp = MR + (size_t)row * 1024 + col;
;                     if (mi < 6) {
;                         if (br > 0) { const u32x2 o = mpk[mi < 6 ? mi : 0][ni]; v.x += bflo(o.x); v.y += bfhi(o.x); v.z += bflo(o.y); v.w += bfhi(o.y); }
;                         u32x2 pk; pk.x = pk2(v.x, v.y); pk.y = pk2(v.z, v.w); mpk[mi < 6 ? mi : 0][ni] = pk;
;                         if (br == 2) *(u32x2*)mp = pk;
.LBB0_1158:
	v_mov_b64_e32 v[84:85], s[60:61]
	v_mad_i64_i32 v[84:85], s[16:17], v86, s5, v[84:85]
	v_lshl_add_u64 v[84:85], v[84:85], 0, v[80:81]
	s_and_b64 vcc, exec, s[38:39]
	s_waitcnt vmcnt(0)
	v_mov_b32_e32 v88, v234
	v_mov_b32_e32 v89, v235
	v_lshlrev_b32_e32 v90, 16, v88
	v_and_b32_e32 v91, 0xffff0000, v88
	v_lshlrev_b32_e32 v88, 16, v89
	v_and_b32_e32 v89, 0xffff0000, v89
	v_pk_mul_f32 v[90:91], v[82:83], v[90:91] op_sel_hi:[0,1]
	v_pk_mul_f32 v[88:89], v[82:83], v[88:89] op_sel_hi:[0,1]
	v_pk_mul_f32 v[78:79], v[78:79], v[88:89]
	v_pk_mul_f32 v[88:89], v[76:77], v[90:91]
	s_cbranch_vccnz .LBB0_1160
	v_lshlrev_b32_e32 v76, 16, v154
	v_and_b32_e32 v77, 0xffff0000, v154
	v_pk_add_f32 v[88:89], v[88:89], v[76:77]
	v_lshlrev_b32_e32 v76, 16, v155
	v_and_b32_e32 v77, 0xffff0000, v155
	v_pk_add_f32 v[78:79], v[78:79], v[76:77]

; __device__ __forceinline__ unsigned pk2(float lo, float hi) { f32x2 v = {lo, hi}; bf16x2_t b = __builtin_convertvector(v, bf16x2_t); return __builtin_bit_cast(unsigned, b); }
; __device__ __forceinline__ float bflo(unsigned u) { return __uint_as_float(u << 16); }
; __device__ __forceinline__ float bfhi(unsigned u) { return __uint_as_float(u & 0xffff0000u); }
; __device__ void merge_phase(const Params& p, int l, unsigned char* smem) {
;     ...
;             for (int mi = 0; mi < 8; ++mi) {
;                 const int row = m0 + wm * 128 + mi * 16 + idx;
;                 const float rs = (br == 2) ? rstd[row] : 1.f;
; #pragma unroll
;                 for (int ni = 0; ni < 4; ++ni) {
;                     const int col = n0 + wn * 64 + ni * 16 + 4 * kq;
;                     const u32x2 g = *(const u32x2*)(MG + (size_t)row * 3072 + br * 1024 + col);
;                     f32x4 gv; gv.x = bflo(g.x); gv.y = bfhi(g.x); gv.z = bflo(g.y); gv.w = bfhi(g.y);
;                     f32x4 v = gv * rs * acc[mi][ni];
;                     bf16_t* mp = MR + (size_t)row * 1024 + col;
;                     if (mi < 6) {
;                         if (br > 0) { const u32x2 o = mpk[mi < 6 ? mi : 0][ni]; v.x += bflo(o.x); v.y += bfhi(o.x); v.z += bflo(o.y); v.w += bfhi(o.y); }
;                         u32x2 pk; pk.x = pk2(v.x, v.y); pk.y = pk2(v.z, v.w); mpk[mi < 6 ? mi : 0][ni] = pk;
;                         if (br == 2) *(u32x2*)mp = pk;
.LBB0_1162:
	v_mov_b32_e32 v83, v82
	v_mov_b32_e32 v86, v82
	v_mov_b32_e32 v87, v82
	s_and_b64 vcc, exec, s[38:39]
	v_mov_b32_e32 v78, v236
	v_mov_b32_e32 v79, v237
	v_lshlrev_b32_e32 v88, 16, v78
	v_and_b32_e32 v89, 0xffff0000, v78
	v_lshlrev_b32_e32 v78, 16, v79
	v_and_b32_e32 v79, 0xffff0000, v79
	v_pk_mul_f32 v[88:89], v[82:83], v[88:89]
	v_pk_mul_f32 v[78:79], v[86:87], v[78:79]
	v_pk_mul_f32 v[72:73], v[72:73], v[88:89]
	v_pk_mul_f32 v[74:75], v[74:75], v[78:79]
	s_cbranch_vccnz .LBB0_1164
	v_lshlrev_b32_e32 v78, 16, v150
	v_and_b32_e32 v79, 0xffff0000, v150
	v_pk_add_f32 v[72:73], v[72:73], v[78:79]
	v_lshlrev_b32_e32 v78, 16, v151
	v_and_b32_e32 v79, 0xffff0000, v151
	v_pk_add_f32 v[74:75], v[74:75], v[78:79]

; __device__ __forceinline__ unsigned pk2(float lo, float hi) { f32x2 v = {lo, hi}; bf16x2_t b = __builtin_convertvector(v, bf16x2_t); return __builtin_bit_cast(unsigned, b); }
; __device__ __forceinline__ float bflo(unsigned u) { return __uint_as_float(u << 16); }
; __device__ __forceinline__ float bfhi(unsigned u) { return __uint_as_float(u & 0xffff0000u); }
; __device__ void merge_phase(const Params& p, int l, unsigned char* smem) {
;     ...
;             for (int mi = 0; mi < 8; ++mi) {
;                 const int row = m0 + wm * 128 + mi * 16 + idx;
;                 const float rs = (br == 2) ? rstd[row] : 1.f;
; #pragma unroll
;                 for (int ni = 0; ni < 4; ++ni) {
;                     const int col = n0 + wn * 64 + ni * 16 + 4 * kq;
;                     const u32x2 g = *(const u32x2*)(MG + (size_t)row * 3072 + br * 1024 + col);
;                     f32x4 gv; gv.x = bflo(g.x); gv.y = bfhi(g.x); gv.z = bflo(g.y); gv.w = bfhi(g.y);
;                     f32x4 v = gv * rs * acc[mi][ni];
;                     bf16_t* mp = MR + (size_t)row * 1024 + col;
;                     if (mi < 6) {
;                         if (br > 0) { const u32x2 o = mpk[mi < 6 ? mi : 0][ni]; v.x += bflo(o.x); v.y += bfhi(o.x); v.z += bflo(o.y); v.w += bfhi(o.y); }
;                         u32x2 pk; pk.x = pk2(v.x, v.y); pk.y = pk2(v.z, v.w); mpk[mi < 6 ? mi : 0][ni] = pk;
;                         if (br == 2) *(u32x2*)mp = pk;
.LBB0_1166:
	v_mov_b32_e32 v74, v82
	v_mov_b32_e32 v75, v82
	s_and_b64 vcc, exec, s[38:39]
	v_mov_b32_e32 v72, v238
	v_mov_b32_e32 v73, v239
	v_lshlrev_b32_e32 v78, 16, v72
	v_and_b32_e32 v79, 0xffff0000, v72
	v_lshlrev_b32_e32 v72, 16, v73
	v_and_b32_e32 v73, 0xffff0000, v73
	v_pk_mul_f32 v[78:79], v[82:83], v[78:79]
	v_pk_mul_f32 v[72:73], v[74:75], v[72:73]
	v_pk_mul_f32 v[68:69], v[68:69], v[78:79]
	v_pk_mul_f32 v[70:71], v[70:71], v[72:73]
	s_cbranch_vccnz .LBB0_1168
	v_lshlrev_b32_e32 v72, 16, v148
	v_and_b32_e32 v73, 0xffff0000, v148
	v_pk_add_f32 v[68:69], v[68:69], v[72:73]
	v_lshlrev_b32_e32 v72, 16, v149
	v_and_b32_e32 v73, 0xffff0000, v149
	v_pk_add_f32 v[70:71], v[70:71], v[72:73]

; __device__ __forceinline__ unsigned pk2(float lo, float hi) { f32x2 v = {lo, hi}; bf16x2_t b = __builtin_convertvector(v, bf16x2_t); return __builtin_bit_cast(unsigned, b); }
; __device__ __forceinline__ float bflo(unsigned u) { return __uint_as_float(u << 16); }
; __device__ __forceinline__ float bfhi(unsigned u) { return __uint_as_float(u & 0xffff0000u); }
; __device__ void merge_phase(const Params& p, int l, unsigned char* smem) {
;     ...
;             for (int mi = 0; mi < 8; ++mi) {
;                 const int row = m0 + wm * 128 + mi * 16 + idx;
;                 const float rs = (br == 2) ? rstd[row] : 1.f;
; #pragma unroll
;                 for (int ni = 0; ni < 4; ++ni) {
;                     const int col = n0 + wn * 64 + ni * 16 + 4 * kq;
;                     const u32x2 g = *(const u32x2*)(MG + (size_t)row * 3072 + br * 1024 + col);
;                     f32x4 gv; gv.x = bflo(g.x); gv.y = bfhi(g.x); gv.z = bflo(g.y); gv.w = bfhi(g.y);
;                     f32x4 v = gv * rs * acc[mi][ni];
;                     bf16_t* mp = MR + (size_t)row * 1024 + col;
;                     if (mi < 6) {
;                         if (br > 0) { const u32x2 o = mpk[mi < 6 ? mi : 0][ni]; v.x += bflo(o.x); v.y += bfhi(o.x); v.z += bflo(o.y); v.w += bfhi(o.y); }
;                         u32x2 pk; pk.x = pk2(v.x, v.y); pk.y = pk2(v.z, v.w); mpk[mi < 6 ? mi : 0][ni] = pk;
;                         if (br == 2) *(u32x2*)mp = pk;
.LBB0_1170:
	s_and_b64 vcc, exec, s[38:39]
	v_mov_b32_e32 v68, v240
	v_mov_b32_e32 v69, v241
	v_lshlrev_b32_e32 v70, 16, v68
	v_and_b32_e32 v71, 0xffff0000, v68
	v_lshlrev_b32_e32 v68, 16, v69
	v_and_b32_e32 v69, 0xffff0000, v69
	v_pk_mul_f32 v[70:71], v[82:83], v[70:71]
	v_mov_b32_e32 v83, v82
	v_pk_mul_f32 v[68:69], v[82:83], v[68:69]
	v_pk_mul_f32 v[64:65], v[64:65], v[70:71]
	v_pk_mul_f32 v[66:67], v[66:67], v[68:69]
	s_cbranch_vccnz .LBB0_1172
	v_lshlrev_b32_e32 v68, 16, v144
	v_and_b32_e32 v69, 0xffff0000, v144
	v_pk_add_f32 v[64:65], v[64:65], v[68:69]
	v_lshlrev_b32_e32 v68, 16, v145
	v_and_b32_e32 v69, 0xffff0000, v145
	v_pk_add_f32 v[66:67], v[66:67], v[68:69]

; __device__ __forceinline__ unsigned pk2(float lo, float hi) { f32x2 v = {lo, hi}; bf16x2_t b = __builtin_convertvector(v, bf16x2_t); return __builtin_bit_cast(unsigned, b); }
; __device__ __forceinline__ float bflo(unsigned u) { return __uint_as_float(u << 16); }
; __device__ __forceinline__ float bfhi(unsigned u) { return __uint_as_float(u & 0xffff0000u); }
; __device__ void merge_phase(const Params& p, int l, unsigned char* smem) {
;     ...
;             for (int mi = 0; mi < 8; ++mi) {
;                 const int row = m0 + wm * 128 + mi * 16 + idx;
;                 const float rs = (br == 2) ? rstd[row] : 1.f;
; #pragma unroll
;                 for (int ni = 0; ni < 4; ++ni) {
;                     const int col = n0 + wn * 64 + ni * 16 + 4 * kq;
;                     const u32x2 g = *(const u32x2*)(MG + (size_t)row * 3072 + br * 1024 + col);
;                     f32x4 gv; gv.x = bflo(g.x); gv.y = bfhi(g.x); gv.z = bflo(g.y); gv.w = bfhi(g.y);
;                     f32x4 v = gv * rs * acc[mi][ni];
;                     bf16_t* mp = MR + (size_t)row * 1024 + col;
;                     if (mi < 6) {
;                         if (br > 0) { const u32x2 o = mpk[mi < 6 ? mi : 0][ni]; v.x += bflo(o.x); v.y += bfhi(o.x); v.z += bflo(o.y); v.w += bfhi(o.y); }
;                         u32x2 pk; pk.x = pk2(v.x, v.y); pk.y = pk2(v.z, v.w); mpk[mi < 6 ? mi : 0][ni] = pk;
;                         if (br == 2) *(u32x2*)mp = pk;
.LBB0_1176:
	v_mov_b64_e32 v[66:67], s[60:61]
	v_mad_i64_i32 v[66:67], s[16:17], v68, s5, v[66:67]
	v_lshl_add_u64 v[66:67], v[66:67], 0, v[80:81]
	s_and_b64 vcc, exec, s[38:39]
	s_waitcnt vmcnt(0)
	v_mov_b32_e32 v70, v242
	v_mov_b32_e32 v71, v243
	v_lshlrev_b32_e32 v72, 16, v70
	v_and_b32_e32 v73, 0xffff0000, v70
	v_lshlrev_b32_e32 v70, 16, v71
	v_and_b32_e32 v71, 0xffff0000, v71
	v_pk_mul_f32 v[72:73], v[64:65], v[72:73] op_sel_hi:[0,1]
	v_pk_mul_f32 v[70:71], v[64:65], v[70:71] op_sel_hi:[0,1]
	v_pk_mul_f32 v[62:63], v[62:63], v[70:71]
	v_pk_mul_f32 v[70:71], v[60:61], v[72:73]
	s_cbranch_vccnz .LBB0_1178
	v_lshlrev_b32_e32 v60, 16, v146
	v_and_b32_e32 v61, 0xffff0000, v146
	v_pk_add_f32 v[70:71], v[70:71], v[60:61]
	v_lshlrev_b32_e32 v60, 16, v147
	v_and_b32_e32 v61, 0xffff0000, v147
	v_pk_add_f32 v[62:63], v[62:63], v[60:61]

; __device__ __forceinline__ unsigned pk2(float lo, float hi) { f32x2 v = {lo, hi}; bf16x2_t b = __builtin_convertvector(v, bf16x2_t); return __builtin_bit_cast(unsigned, b); }
; __device__ __forceinline__ float bflo(unsigned u) { return __uint_as_float(u << 16); }
; __device__ __forceinline__ float bfhi(unsigned u) { return __uint_as_float(u & 0xffff0000u); }
; __device__ void merge_phase(const Params& p, int l, unsigned char* smem) {
;     ...
;             for (int mi = 0; mi < 8; ++mi) {
;                 const int row = m0 + wm * 128 + mi * 16 + idx;
;                 const float rs = (br == 2) ? rstd[row] : 1.f;
; #pragma unroll
;                 for (int ni = 0; ni < 4; ++ni) {
;                     const int col = n0 + wn * 64 + ni * 16 + 4 * kq;
;                     const u32x2 g = *(const u32x2*)(MG + (size_t)row * 3072 + br * 1024 + col);
;                     f32x4 gv; gv.x = bflo(g.x); gv.y = bfhi(g.x); gv.z = bflo(g.y); gv.w = bfhi(g.y);
;                     f32x4 v = gv * rs * acc[mi][ni];
;                     bf16_t* mp = MR + (size_t)row * 1024 + col;
;                     if (mi < 6) {
;                         if (br > 0) { const u32x2 o = mpk[mi < 6 ? mi : 0][ni]; v.x += bflo(o.x); v.y += bfhi(o.x); v.z += bflo(o.y); v.w += bfhi(o.y); }
;                         u32x2 pk; pk.x = pk2(v.x, v.y); pk.y = pk2(v.z, v.w); mpk[mi < 6 ? mi : 0][ni] = pk;
;                         if (br == 2) *(u32x2*)mp = pk;
.LBB0_1180:
	v_mov_b32_e32 v65, v64
	v_mov_b32_e32 v68, v64
	v_mov_b32_e32 v69, v64
	s_and_b64 vcc, exec, s[38:39]
	v_mov_b32_e32 v62, v244
	v_mov_b32_e32 v63, v245
	v_lshlrev_b32_e32 v70, 16, v62
	v_and_b32_e32 v71, 0xffff0000, v62
	v_lshlrev_b32_e32 v62, 16, v63
	v_and_b32_e32 v63, 0xffff0000, v63
	v_pk_mul_f32 v[70:71], v[64:65], v[70:71]
	v_pk_mul_f32 v[62:63], v[68:69], v[62:63]
	v_pk_mul_f32 v[56:57], v[56:57], v[70:71]
	v_pk_mul_f32 v[58:59], v[58:59], v[62:63]
	s_cbranch_vccnz .LBB0_1182
	v_lshlrev_b32_e32 v62, 16, v142
	v_and_b32_e32 v63, 0xffff0000, v142
	v_pk_add_f32 v[56:57], v[56:57], v[62:63]
	v_lshlrev_b32_e32 v62, 16, v143
	v_and_b32_e32 v63, 0xffff0000, v143
	v_pk_add_f32 v[58:59], v[58:59], v[62:63]

; __device__ __forceinline__ unsigned pk2(float lo, float hi) { f32x2 v = {lo, hi}; bf16x2_t b = __builtin_convertvector(v, bf16x2_t); return __builtin_bit_cast(unsigned, b); }
; __device__ __forceinline__ float bflo(unsigned u) { return __uint_as_float(u << 16); }
; __device__ __forceinline__ float bfhi(unsigned u) { return __uint_as_float(u & 0xffff0000u); }
; __device__ void merge_phase(const Params& p, int l, unsigned char* smem) {
;     ...
;             for (int mi = 0; mi < 8; ++mi) {
;                 const int row = m0 + wm * 128 + mi * 16 + idx;
;                 const float rs = (br == 2) ? rstd[row] : 1.f;
; #pragma unroll
;                 for (int ni = 0; ni < 4; ++ni) {
;                     const int col = n0 + wn * 64 + ni * 16 + 4 * kq;
;                     const u32x2 g = *(const u32x2*)(MG + (size_t)row * 3072 + br * 1024 + col);
;                     f32x4 gv; gv.x = bflo(g.x); gv.y = bfhi(g.x); gv.z = bflo(g.y); gv.w = bfhi(g.y);
;                     f32x4 v = gv * rs * acc[mi][ni];
;                     bf16_t* mp = MR + (size_t)row * 1024 + col;
;                     if (mi < 6) {
;                         if (br > 0) { const u32x2 o = mpk[mi < 6 ? mi : 0][ni]; v.x += bflo(o.x); v.y += bfhi(o.x); v.z += bflo(o.y); v.w += bfhi(o.y); }
;                         u32x2 pk; pk.x = pk2(v.x, v.y); pk.y = pk2(v.z, v.w); mpk[mi < 6 ? mi : 0][ni] = pk;
;                         if (br == 2) *(u32x2*)mp = pk;
.LBB0_1184:
	v_mov_b32_e32 v58, v64
	v_mov_b32_e32 v59, v64
	s_and_b64 vcc, exec, s[38:39]
	v_mov_b32_e32 v56, v246
	v_mov_b32_e32 v57, v247
	v_lshlrev_b32_e32 v62, 16, v56
	v_and_b32_e32 v63, 0xffff0000, v56
	v_lshlrev_b32_e32 v56, 16, v57
	v_and_b32_e32 v57, 0xffff0000, v57
	v_pk_mul_f32 v[62:63], v[64:65], v[62:63]
	v_pk_mul_f32 v[56:57], v[58:59], v[56:57]
	v_pk_mul_f32 v[52:53], v[52:53], v[62:63]
	v_pk_mul_f32 v[54:55], v[54:55], v[56:57]
	s_cbranch_vccnz .LBB0_1186
	v_lshlrev_b32_e32 v56, 16, v140
	v_and_b32_e32 v57, 0xffff0000, v140
	v_pk_add_f32 v[52:53], v[52:53], v[56:57]
	v_lshlrev_b32_e32 v56, 16, v141
	v_and_b32_e32 v57, 0xffff0000, v141
	v_pk_add_f32 v[54:55], v[54:55], v[56:57]

; __device__ __forceinline__ unsigned pk2(float lo, float hi) { f32x2 v = {lo, hi}; bf16x2_t b = __builtin_convertvector(v, bf16x2_t); return __builtin_bit_cast(unsigned, b); }
; __device__ __forceinline__ float bflo(unsigned u) { return __uint_as_float(u << 16); }
; __device__ __forceinline__ float bfhi(unsigned u) { return __uint_as_float(u & 0xffff0000u); }
; __device__ void merge_phase(const Params& p, int l, unsigned char* smem) {
;     ...
;             for (int mi = 0; mi < 8; ++mi) {
;                 const int row = m0 + wm * 128 + mi * 16 + idx;
;                 const float rs = (br == 2) ? rstd[row] : 1.f;
; #pragma unroll
;                 for (int ni = 0; ni < 4; ++ni) {
;                     const int col = n0 + wn * 64 + ni * 16 + 4 * kq;
;                     const u32x2 g = *(const u32x2*)(MG + (size_t)row * 3072 + br * 1024 + col);
;                     f32x4 gv; gv.x = bflo(g.x); gv.y = bfhi(g.x); gv.z = bflo(g.y); gv.w = bfhi(g.y);
;                     f32x4 v = gv * rs * acc[mi][ni];
;                     bf16_t* mp = MR + (size_t)row * 1024 + col;
;                     if (mi < 6) {
;                         if (br > 0) { const u32x2 o = mpk[mi < 6 ? mi : 0][ni]; v.x += bflo(o.x); v.y += bfhi(o.x); v.z += bflo(o.y); v.w += bfhi(o.y); }
;                         u32x2 pk; pk.x = pk2(v.x, v.y); pk.y = pk2(v.z, v.w); mpk[mi < 6 ? mi : 0][ni] = pk;
;                         if (br == 2) *(u32x2*)mp = pk;
.LBB0_1188:
	s_and_b64 vcc, exec, s[38:39]
	v_mov_b32_e32 v52, v248
	v_mov_b32_e32 v53, v249
	v_lshlrev_b32_e32 v54, 16, v52
	v_and_b32_e32 v55, 0xffff0000, v52
	v_lshlrev_b32_e32 v52, 16, v53
	v_and_b32_e32 v53, 0xffff0000, v53
	v_pk_mul_f32 v[54:55], v[64:65], v[54:55]
	v_mov_b32_e32 v65, v64
	v_pk_mul_f32 v[52:53], v[64:65], v[52:53]
	v_pk_mul_f32 v[48:49], v[48:49], v[54:55]
	v_pk_mul_f32 v[50:51], v[50:51], v[52:53]
	s_cbranch_vccnz .LBB0_1190
	v_lshlrev_b32_e32 v52, 16, v136
	v_and_b32_e32 v53, 0xffff0000, v136
	v_pk_add_f32 v[48:49], v[48:49], v[52:53]
	v_lshlrev_b32_e32 v52, 16, v137
	v_and_b32_e32 v53, 0xffff0000, v137
	v_pk_add_f32 v[50:51], v[50:51], v[52:53]

; __device__ __forceinline__ unsigned pk2(float lo, float hi) { f32x2 v = {lo, hi}; bf16x2_t b = __builtin_convertvector(v, bf16x2_t); return __builtin_bit_cast(unsigned, b); }
; __device__ __forceinline__ float bflo(unsigned u) { return __uint_as_float(u << 16); }
; __device__ __forceinline__ float bfhi(unsigned u) { return __uint_as_float(u & 0xffff0000u); }
; __device__ void merge_phase(const Params& p, int l, unsigned char* smem) {
;     ...
;             for (int mi = 0; mi < 8; ++mi) {
;                 const int row = m0 + wm * 128 + mi * 16 + idx;
;                 const float rs = (br == 2) ? rstd[row] : 1.f;
; #pragma unroll
;                 for (int ni = 0; ni < 4; ++ni) {
;                     const int col = n0 + wn * 64 + ni * 16 + 4 * kq;
;                     const u32x2 g = *(const u32x2*)(MG + (size_t)row * 3072 + br * 1024 + col);
;                     f32x4 gv; gv.x = bflo(g.x); gv.y = bfhi(g.x); gv.z = bflo(g.y); gv.w = bfhi(g.y);
;                     f32x4 v = gv * rs * acc[mi][ni];
;                     bf16_t* mp = MR + (size_t)row * 1024 + col;
;                     if (mi < 6) {
;                         if (br > 0) { const u32x2 o = mpk[mi < 6 ? mi : 0][ni]; v.x += bflo(o.x); v.y += bfhi(o.x); v.z += bflo(o.y); v.w += bfhi(o.y); }
;                         u32x2 pk; pk.x = pk2(v.x, v.y); pk.y = pk2(v.z, v.w); mpk[mi < 6 ? mi : 0][ni] = pk;
;                         if (br == 2) *(u32x2*)mp = pk;
.LBB0_1194:
	v_mov_b64_e32 v[50:51], s[60:61]
	v_mad_i64_i32 v[50:51], s[16:17], v52, s5, v[50:51]
	v_lshl_add_u64 v[50:51], v[50:51], 0, v[80:81]
	s_and_b64 vcc, exec, s[38:39]
	s_waitcnt vmcnt(0)
	v_mov_b32_e32 v54, v190
	v_mov_b32_e32 v55, v191
	v_lshlrev_b32_e32 v56, 16, v54
	v_and_b32_e32 v57, 0xffff0000, v54
	v_lshlrev_b32_e32 v54, 16, v55
	v_and_b32_e32 v55, 0xffff0000, v55
	v_pk_mul_f32 v[56:57], v[48:49], v[56:57] op_sel_hi:[0,1]
	v_pk_mul_f32 v[54:55], v[48:49], v[54:55] op_sel_hi:[0,1]
	v_pk_mul_f32 v[46:47], v[46:47], v[54:55]
	v_pk_mul_f32 v[54:55], v[44:45], v[56:57]
	s_cbranch_vccnz .LBB0_1196
	v_lshlrev_b32_e32 v44, 16, v138
	v_and_b32_e32 v45, 0xffff0000, v138
	v_pk_add_f32 v[54:55], v[54:55], v[44:45]
	v_lshlrev_b32_e32 v44, 16, v139
	v_and_b32_e32 v45, 0xffff0000, v139
	v_pk_add_f32 v[46:47], v[46:47], v[44:45]

; __device__ __forceinline__ unsigned pk2(float lo, float hi) { f32x2 v = {lo, hi}; bf16x2_t b = __builtin_convertvector(v, bf16x2_t); return __builtin_bit_cast(unsigned, b); }
; __device__ __forceinline__ float bflo(unsigned u) { return __uint_as_float(u << 16); }
; __device__ __forceinline__ float bfhi(unsigned u) { return __uint_as_float(u & 0xffff0000u); }
; __device__ void merge_phase(const Params& p, int l, unsigned char* smem) {
;     ...
;             for (int mi = 0; mi < 8; ++mi) {
;                 const int row = m0 + wm * 128 + mi * 16 + idx;
;                 const float rs = (br == 2) ? rstd[row] : 1.f;
; #pragma unroll
;                 for (int ni = 0; ni < 4; ++ni) {
;                     const int col = n0 + wn * 64 + ni * 16 + 4 * kq;
;                     const u32x2 g = *(const u32x2*)(MG + (size_t)row * 3072 + br * 1024 + col);
;                     f32x4 gv; gv.x = bflo(g.x); gv.y = bfhi(g.x); gv.z = bflo(g.y); gv.w = bfhi(g.y);
;                     f32x4 v = gv * rs * acc[mi][ni];
;                     bf16_t* mp = MR + (size_t)row * 1024 + col;
;                     if (mi < 6) {
;                         if (br > 0) { const u32x2 o = mpk[mi < 6 ? mi : 0][ni]; v.x += bflo(o.x); v.y += bfhi(o.x); v.z += bflo(o.y); v.w += bfhi(o.y); }
;                         u32x2 pk; pk.x = pk2(v.x, v.y); pk.y = pk2(v.z, v.w); mpk[mi < 6 ? mi : 0][ni] = pk;
;                         if (br == 2) *(u32x2*)mp = pk;
.LBB0_1198:
	v_mov_b32_e32 v49, v48
	v_mov_b32_e32 v52, v48
	v_mov_b32_e32 v53, v48
	s_and_b64 vcc, exec, s[38:39]
	v_mov_b32_e32 v46, v192
	v_mov_b32_e32 v47, v193
	v_lshlrev_b32_e32 v54, 16, v46
	v_and_b32_e32 v55, 0xffff0000, v46
	v_lshlrev_b32_e32 v46, 16, v47
	v_and_b32_e32 v47, 0xffff0000, v47
	v_pk_mul_f32 v[54:55], v[48:49], v[54:55]
	v_pk_mul_f32 v[46:47], v[52:53], v[46:47]
	v_pk_mul_f32 v[40:41], v[40:41], v[54:55]
	v_pk_mul_f32 v[42:43], v[42:43], v[46:47]
	s_cbranch_vccnz .LBB0_1200
	v_lshlrev_b32_e32 v46, 16, v134
	v_and_b32_e32 v47, 0xffff0000, v134
	v_pk_add_f32 v[40:41], v[40:41], v[46:47]
	v_lshlrev_b32_e32 v46, 16, v135
	v_and_b32_e32 v47, 0xffff0000, v135
	v_pk_add_f32 v[42:43], v[42:43], v[46:47]

; __device__ __forceinline__ unsigned pk2(float lo, float hi) { f32x2 v = {lo, hi}; bf16x2_t b = __builtin_convertvector(v, bf16x2_t); return __builtin_bit_cast(unsigned, b); }
; __device__ __forceinline__ float bflo(unsigned u) { return __uint_as_float(u << 16); }
; __device__ __forceinline__ float bfhi(unsigned u) { return __uint_as_float(u & 0xffff0000u); }
; __device__ void merge_phase(const Params& p, int l, unsigned char* smem) {
;     ...
;             for (int mi = 0; mi < 8; ++mi) {
;                 const int row = m0 + wm * 128 + mi * 16 + idx;
;                 const float rs = (br == 2) ? rstd[row] : 1.f;
; #pragma unroll
;                 for (int ni = 0; ni < 4; ++ni) {
;                     const int col = n0 + wn * 64 + ni * 16 + 4 * kq;
;                     const u32x2 g = *(const u32x2*)(MG + (size_t)row * 3072 + br * 1024 + col);
;                     f32x4 gv; gv.x = bflo(g.x); gv.y = bfhi(g.x); gv.z = bflo(g.y); gv.w = bfhi(g.y);
;                     f32x4 v = gv * rs * acc[mi][ni];
;                     bf16_t* mp = MR + (size_t)row * 1024 + col;
;                     if (mi < 6) {
;                         if (br > 0) { const u32x2 o = mpk[mi < 6 ? mi : 0][ni]; v.x += bflo(o.x); v.y += bfhi(o.x); v.z += bflo(o.y); v.w += bfhi(o.y); }
;                         u32x2 pk; pk.x = pk2(v.x, v.y); pk.y = pk2(v.z, v.w); mpk[mi < 6 ? mi : 0][ni] = pk;
;                         if (br == 2) *(u32x2*)mp = pk;
.LBB0_1202:
	v_mov_b32_e32 v42, v48
	v_mov_b32_e32 v43, v48
	s_and_b64 vcc, exec, s[38:39]
	v_mov_b32_e32 v40, v194
	v_mov_b32_e32 v41, v195
	v_lshlrev_b32_e32 v46, 16, v40
	v_and_b32_e32 v47, 0xffff0000, v40
	v_lshlrev_b32_e32 v40, 16, v41
	v_and_b32_e32 v41, 0xffff0000, v41
	v_pk_mul_f32 v[46:47], v[48:49], v[46:47]
	v_pk_mul_f32 v[40:41], v[42:43], v[40:41]
	v_pk_mul_f32 v[36:37], v[36:37], v[46:47]
	v_pk_mul_f32 v[38:39], v[38:39], v[40:41]
	s_cbranch_vccnz .LBB0_1204
	v_lshlrev_b32_e32 v40, 16, v132
	v_and_b32_e32 v41, 0xffff0000, v132
	v_pk_add_f32 v[36:37], v[36:37], v[40:41]
	v_lshlrev_b32_e32 v40, 16, v133
	v_and_b32_e32 v41, 0xffff0000, v133
	v_pk_add_f32 v[38:39], v[38:39], v[40:41]

; __device__ __forceinline__ unsigned pk2(float lo, float hi) { f32x2 v = {lo, hi}; bf16x2_t b = __builtin_convertvector(v, bf16x2_t); return __builtin_bit_cast(unsigned, b); }
; __device__ __forceinline__ float bflo(unsigned u) { return __uint_as_float(u << 16); }
; __device__ __forceinline__ float bfhi(unsigned u) { return __uint_as_float(u & 0xffff0000u); }
; __device__ void merge_phase(const Params& p, int l, unsigned char* smem) {
;     ...
;             for (int mi = 0; mi < 8; ++mi) {
;                 const int row = m0 + wm * 128 + mi * 16 + idx;
;                 const float rs = (br == 2) ? rstd[row] : 1.f;
; #pragma unroll
;                 for (int ni = 0; ni < 4; ++ni) {
;                     const int col = n0 + wn * 64 + ni * 16 + 4 * kq;
;                     const u32x2 g = *(const u32x2*)(MG + (size_t)row * 3072 + br * 1024 + col);
;                     f32x4 gv; gv.x = bflo(g.x); gv.y = bfhi(g.x); gv.z = bflo(g.y); gv.w = bfhi(g.y);
;                     f32x4 v = gv * rs * acc[mi][ni];
;                     bf16_t* mp = MR + (size_t)row * 1024 + col;
;                     if (mi < 6) {
;                         if (br > 0) { const u32x2 o = mpk[mi < 6 ? mi : 0][ni]; v.x += bflo(o.x); v.y += bfhi(o.x); v.z += bflo(o.y); v.w += bfhi(o.y); }
;                         u32x2 pk; pk.x = pk2(v.x, v.y); pk.y = pk2(v.z, v.w); mpk[mi < 6 ? mi : 0][ni] = pk;
;                         if (br == 2) *(u32x2*)mp = pk;
.LBB0_1206:
	s_and_b64 vcc, exec, s[38:39]
	v_mov_b32_e32 v36, v196
	v_mov_b32_e32 v37, v197
	v_lshlrev_b32_e32 v38, 16, v36
	v_and_b32_e32 v39, 0xffff0000, v36
	v_lshlrev_b32_e32 v36, 16, v37
	v_and_b32_e32 v37, 0xffff0000, v37
	v_pk_mul_f32 v[38:39], v[48:49], v[38:39]
	v_mov_b32_e32 v49, v48
	v_pk_mul_f32 v[36:37], v[48:49], v[36:37]
	v_pk_mul_f32 v[32:33], v[32:33], v[38:39]
	v_pk_mul_f32 v[34:35], v[34:35], v[36:37]
	s_cbranch_vccnz .LBB0_1208
	v_lshlrev_b32_e32 v36, 16, v130
	v_and_b32_e32 v37, 0xffff0000, v130
	v_pk_add_f32 v[32:33], v[32:33], v[36:37]
	v_lshlrev_b32_e32 v36, 16, v131
	v_and_b32_e32 v37, 0xffff0000, v131
	v_pk_add_f32 v[34:35], v[34:35], v[36:37]
